# spatial gating: causal-weight tile build rewritten branch-free (all 8 weight loads and 32 rstd LDS reads issued up front, masked with v_cndmask instead of 32 exec-masked load-wait-multiply steps)
# speedup vs baseline: 1.0049x; 1.0047x over previous
; #define LAS __attribute__((address_space(3)))
; __device__ __forceinline__ u32x4 pack8(const float* v) { u32x4 w; w.x = cvt_pk_bf16(v[0], v[1]); w.y = cvt_pk_bf16(v[2], v[3]); w.z = cvt_pk_bf16(v[4], v[5]); w.w = cvt_pk_bf16(v[6], v[7]); return w; }
; __device__ __forceinline__ void sg_phase(const float* sgw, const float* sgb, const float* sgn, const bf16_t* U, const bf16_t* VTc, const float* ssv, bf16_t* GATED, LAS unsigned char* lds, int G) {
;     ...
;             const int t = tid >> 2, sg0 = 32 * (tid & 3);
;             if (sg0 <= t) {
;                 const float* wrow = sgw + ((size_t)g * 128 + t) * 128 + sg0;
; #pragma unroll
;                 for (int c = 0; c < 4; ++c) { const f32x4 wa = *(const f32x4*)(wrow + 8 * c), wb = *(const f32x4*)(wrow + 8 * c + 4); float av[8];
; #pragma unroll
;                     for (int j = 0; j < 8; ++j) { const int s = sg0 + 8 * c + j; const float w = j < 4 ? wa[j] : wb[j - 4]; av[j] = (s <= t) ? w * tab[s] : 0.f; }
;                     *(LAS u32x4*)(lds + t * WROW + (sg0 + 8 * c) * 2) = pack8(av); }
;             }
.LBB0_523:
	s_or_b64 exec, exec, vcc
	s_lshl_b32 s93, s93, 7
	s_waitcnt lgkmcnt(0)
	s_barrier
	s_and_saveexec_b64 vcc, s[8:9]
	s_cbranch_execz .LBB0_520
	v_add_u32_e32 v64, s93, v91
	v_lshlrev_b64 v[44:45], 9, v[64:65]
	v_lshl_add_u64 v[86:87], v[80:81], 0, v[44:45]
	v_readlane_b32 s76, v255, 9
	v_readlane_b32 s77, v255, 10
	global_load_dwordx4 v[120:123], v[86:87], off
	global_load_dwordx4 v[124:127], v[86:87], off offset:16
	global_load_dwordx4 v[128:131], v[86:87], off offset:32
	global_load_dwordx4 v[132:135], v[86:87], off offset:48
	global_load_dwordx4 v[136:139], v[86:87], off offset:64
	global_load_dwordx4 v[140:143], v[86:87], off offset:80
	global_load_dwordx4 v[144:147], v[86:87], off offset:96
	global_load_dwordx4 v[148:151], v[86:87], off offset:112
	ds_read_b32 v152, v92 offset:36864
	ds_read_b32 v153, v92 offset:36868
	ds_read_b32 v154, v92 offset:36872
	ds_read_b32 v155, v92 offset:36876
	ds_read_b32 v156, v92 offset:36880
	ds_read_b32 v157, v92 offset:36884
	ds_read_b32 v158, v92 offset:36888
	ds_read_b32 v159, v92 offset:36892
	ds_read_b32 v160, v92 offset:36896
	ds_read_b32 v161, v92 offset:36900
	ds_read_b32 v162, v92 offset:36904
	ds_read_b32 v163, v92 offset:36908
	ds_read_b32 v164, v92 offset:36912
	ds_read_b32 v165, v92 offset:36916
	ds_read_b32 v166, v92 offset:36920
	ds_read_b32 v167, v92 offset:36924
	ds_read_b32 v168, v92 offset:36928
	ds_read_b32 v169, v92 offset:36932
	ds_read_b32 v170, v92 offset:36936
	ds_read_b32 v171, v92 offset:36940
	ds_read_b32 v172, v92 offset:36944
	ds_read_b32 v173, v92 offset:36948
	ds_read_b32 v174, v92 offset:36952
	ds_read_b32 v175, v92 offset:36956
	ds_read_b32 v176, v92 offset:36960
	ds_read_b32 v177, v92 offset:36964
	ds_read_b32 v178, v92 offset:36968
	ds_read_b32 v179, v92 offset:36972
	ds_read_b32 v202, v92 offset:36976
	ds_read_b32 v203, v92 offset:36980
	ds_read_b32 v204, v92 offset:36984
	ds_read_b32 v205, v92 offset:36988
	s_waitcnt vmcnt(0) lgkmcnt(0)
	v_mul_f32_e32 v120, v120, v152
	v_mul_f32_e32 v121, v121, v153
	v_mul_f32_e32 v122, v122, v154
	v_mul_f32_e32 v123, v123, v155
	v_mul_f32_e32 v124, v124, v156
	v_mul_f32_e32 v125, v125, v157
	v_mul_f32_e32 v126, v126, v158
	v_mul_f32_e32 v127, v127, v159
	v_mul_f32_e32 v128, v128, v160
	v_mul_f32_e32 v129, v129, v161
	v_mul_f32_e32 v130, v130, v162
	v_mul_f32_e32 v131, v131, v163
	v_mul_f32_e32 v132, v132, v164
	v_mul_f32_e32 v133, v133, v165
	v_mul_f32_e32 v134, v134, v166
	v_mul_f32_e32 v135, v135, v167
	v_mul_f32_e32 v136, v136, v168
	v_mul_f32_e32 v137, v137, v169
	v_mul_f32_e32 v138, v138, v170
	v_mul_f32_e32 v139, v139, v171
	v_mul_f32_e32 v140, v140, v172
	v_mul_f32_e32 v141, v141, v173
	v_mul_f32_e32 v142, v142, v174
	v_mul_f32_e32 v143, v143, v175
	v_mul_f32_e32 v144, v144, v176
	v_mul_f32_e32 v145, v145, v177
	v_mul_f32_e32 v146, v146, v178
	v_mul_f32_e32 v147, v147, v179
	v_mul_f32_e32 v148, v148, v202
	v_mul_f32_e32 v149, v149, v203
	v_mul_f32_e32 v150, v150, v204
	v_mul_f32_e32 v151, v151, v205
	v_cndmask_b32_e64 v121, 0, v121, s[76:77]
	v_cndmask_b32_e64 v122, 0, v122, s[12:13]
	v_cndmask_b32_e64 v123, 0, v123, s[14:15]
	v_cndmask_b32_e64 v124, 0, v124, s[16:17]
	v_cndmask_b32_e64 v125, 0, v125, s[18:19]
	v_cndmask_b32_e64 v126, 0, v126, s[20:21]
	v_cndmask_b32_e64 v127, 0, v127, s[22:23]
	v_cndmask_b32_e64 v128, 0, v128, s[24:25]
	v_cndmask_b32_e64 v129, 0, v129, s[26:27]
	v_cndmask_b32_e64 v130, 0, v130, s[28:29]
	v_cndmask_b32_e64 v131, 0, v131, s[30:31]
	v_cndmask_b32_e64 v132, 0, v132, s[34:35]
	v_cndmask_b32_e64 v133, 0, v133, s[36:37]
	v_cndmask_b32_e64 v134, 0, v134, s[38:39]
	v_cndmask_b32_e64 v135, 0, v135, s[40:41]
	v_cndmask_b32_e64 v136, 0, v136, s[42:43]
	v_cndmask_b32_e64 v137, 0, v137, s[44:45]
	v_cndmask_b32_e64 v138, 0, v138, s[46:47]
	v_cndmask_b32_e64 v139, 0, v139, s[48:49]
	v_cndmask_b32_e64 v140, 0, v140, s[50:51]
	v_cndmask_b32_e64 v141, 0, v141, s[52:53]
	v_cndmask_b32_e64 v142, 0, v142, s[54:55]
	v_cndmask_b32_e64 v143, 0, v143, s[56:57]
	v_cndmask_b32_e64 v144, 0, v144, s[58:59]
	v_cndmask_b32_e64 v145, 0, v145, s[60:61]
	v_cndmask_b32_e64 v146, 0, v146, s[62:63]
	v_cndmask_b32_e64 v147, 0, v147, s[64:65]
	v_cndmask_b32_e64 v148, 0, v148, s[66:67]
	v_cndmask_b32_e64 v149, 0, v149, s[68:69]
	v_cndmask_b32_e64 v150, 0, v150, s[70:71]
	v_cndmask_b32_e64 v151, 0, v151, s[72:73]
	v_cvt_pk_bf16_f32 v152, v120, v121
	v_cvt_pk_bf16_f32 v153, v122, v123
	v_cvt_pk_bf16_f32 v154, v124, v125
	v_cvt_pk_bf16_f32 v155, v126, v127
	v_cvt_pk_bf16_f32 v156, v128, v129
	v_cvt_pk_bf16_f32 v157, v130, v131
	v_cvt_pk_bf16_f32 v158, v132, v133
	v_cvt_pk_bf16_f32 v159, v134, v135
	v_cvt_pk_bf16_f32 v160, v136, v137
	v_cvt_pk_bf16_f32 v161, v138, v139
	v_cvt_pk_bf16_f32 v162, v140, v141
	v_cvt_pk_bf16_f32 v163, v142, v143
	v_cvt_pk_bf16_f32 v164, v144, v145
	v_cvt_pk_bf16_f32 v165, v146, v147
	v_cvt_pk_bf16_f32 v166, v148, v149
	v_cvt_pk_bf16_f32 v167, v150, v151
	ds_write_b128 v94, v[152:155]
	ds_write_b128 v94, v[156:159] offset:16
	ds_write_b128 v94, v[160:163] offset:32
	ds_write_b128 v94, v[164:167] offset:48
	s_branch .LBB0_520
